# NA bias table zero-padded in LDS: per-element index clamps removed (one ds_read with immediate offset per bias)
# speedup vs baseline: 1.0515x; 1.0004x over previous
; template <int DQK, bool NA, bool SMAX, int LDV> ...
;     ...
;   if (NA) { for (int i = tid; i < 465; i += 512) rpbl[i] = rpb_g[i] * LOG2E; }
.LBB0_1048:
	s_and_b64 vcc, exec, s[0:1]
	s_cbranch_vccz .LBB0_1100
	v_mov_b32_e32 v2, v149
	s_movk_i32 s0, 0x1d1
	s_nop 0
	v_cmp_gt_i32_e32 vcc, s0, v2
	s_and_saveexec_b64 s[0:1], vcc
	s_cbranch_execz .LBB0_1057
	v_max_i32_e32 v0, 0xffffffd1, v2
	v_sub_u32_e32 v0, v0, v2
	v_add_u32_e32 v0, 0x1ff, v0
	s_movk_i32 s26, 0x1ff
	v_cmp_lt_u32_e32 vcc, s26, v0
	s_mov_b64 s[40:41], -1
	v_mov_b32_e32 v4, v2
	s_and_saveexec_b64 s[26:27], vcc
	s_cbranch_execz .LBB0_1054
	v_lshrrev_b32_e32 v0, 9, v0
	v_add_u32_e32 v0, 1, v0
	v_and_b32_e32 v6, 0xfffffe, v0
	v_add_u32_e32 v3, 0x200, v2
	s_add_i32 s33, 0, 0xa400
	v_lshl_add_u32 v7, v2, 2, s33
	s_mov_b64 s[40:41], 0
	v_mov_b32_e32 v8, v6
	v_mov_b64_e32 v[4:5], v[2:3]
	v_readlane_b32 s42, v254, 33
	v_readlane_b32 s43, v254, 34
.LBB0_1052:
	v_ashrrev_i32_e32 v13, 31, v4
	v_mov_b32_e32 v12, v4
	v_ashrrev_i32_e32 v11, 31, v5
	v_mov_b32_e32 v10, v5
	v_lshl_add_u64 v[12:13], v[12:13], 2, s[4:5]
	v_lshl_add_u64 v[10:11], v[10:11], 2, s[4:5]
	global_load_dword v12, v[12:13], off
	s_nop 0
	global_load_dword v13, v[10:11], off
	v_add_u32_e32 v8, -2, v8
	v_cmp_eq_u32_e32 vcc, 0, v8
	v_add_u32_e32 v5, 0x400, v5
	v_add_u32_e32 v4, 0x400, v4
	s_or_b64 s[40:41], vcc, s[40:41]
	s_waitcnt vmcnt(0)
	v_fma_f32 v10, v12, s42, -v153
	v_fma_f32 v11, v13, s42, -v153
	ds_write2st64_b32 v7, v10, v11 offset1:8
	v_add_u32_e32 v7, 0x1000, v7
	s_andn2_b64 exec, exec, s[40:41]
	s_cbranch_execnz .LBB0_1052
	s_or_b64 exec, exec, s[40:41]
	v_cmp_ne_u32_e32 vcc, v0, v6
	v_lshl_add_u32 v4, v6, 9, v2
	s_orn2_b64 s[40:41], vcc, exec
.LBB0_1054:
	s_or_b64 exec, exec, s[26:27]
	s_and_b64 s[4:5], exec, s[40:41]
	s_mov_b64 s[40:41], 0x800
	s_mov_b64 exec, s[4:5]
	s_cbranch_execz .LBB0_1057
	s_add_i32 s4, 0, 0xa400
	v_lshl_add_u32 v0, v4, 2, s4
	v_readlane_b32 s64, v249, 20
	v_readlane_b32 s4, v248, 26
	v_readlane_b32 s65, v249, 21
	s_add_u32 s4, s64, s4
	v_readlane_b32 s5, v248, 25
	v_ashrrev_i32_e32 v5, 31, v4
	s_addc_u32 s5, s65, s5
	v_add_u32_e32 v3, 0xfffffe00, v4
	s_movk_i32 s26, 0xffd0
	v_lshl_add_u64 v[4:5], v[4:5], 2, s[4:5]
	s_mov_b64 s[4:5], 0
	v_readlane_b32 s66, v249, 22
	v_readlane_b32 s67, v249, 23
	v_readlane_b32 s68, v249, 24
	v_readlane_b32 s69, v249, 25
	v_readlane_b32 s70, v249, 26
	v_readlane_b32 s71, v249, 27
	v_readlane_b32 s72, v249, 28
	v_readlane_b32 s73, v249, 29
	v_readlane_b32 s74, v249, 30
	v_readlane_b32 s75, v249, 31
	v_readlane_b32 s76, v249, 32
	v_readlane_b32 s77, v249, 33
	v_readlane_b32 s78, v249, 34
	v_readlane_b32 s79, v249, 35
	s_mov_b32 s101, 0x3fb8aa3b

; template <int DQK, bool NA, bool SMAX, int LDV> ...
;     ...
;   if (NA) { for (int i = tid; i < 465; i += 512) rpbl[i] = rpb_g[i] * LOG2E; }
;   bf16x8 qf[2][NDS];
; #pragma unroll
;   for (int qt = 0; qt < 2; ++qt)
; #pragma unroll
;     for (int ds = 0; ds < NDS; ++ds) qf[qt][ds] = *(const bf16x8*)(Qp + (size_t)(w * 32 + qt * 16 + fr) * ldq + ds * 32 + fq * 8);
;   u32x4 rkA[NKC], rvA, rkB[NKC], rvB;
;   int kkey[NKC], kcc[NKC];
;   bool kval[NKC];
; #pragma unroll
;   for (int i = 0; i < NKC; ++i) { const int c = tid + i * 512; kval[i] = c < 64 * CPK; kkey[i] = kval[i] ? c / CPK : 0; kcc[i] = kval[i] ? c - kkey[i] * CPK : 0; }
;   const int vdv = tid >> 3, vcc = tid & 7;
;   {
; #pragma unroll
;     for (int i = 0; i < NKC; ++i) rkA[i] = *(const u32x4*)(Kp + (size_t)kkey[i] * ldk + kcc[i] * 8);
;     rvA = *(const u32x4*)(Vp + (size_t)vdv * LDV + vcc * 8);
;     if (nkt > 1) {
;       const int kb = 64;
; #pragma unroll
;       for (int i = 0; i < NKC; ++i) rkB[i] = *(const u32x4*)(Kp + (size_t)(kb + kkey[i]) * ldk + kcc[i] * 8);
;       rvB = *(const u32x4*)(Vp + (size_t)(kb + vdv) * LDV + vcc * 8);
;     }
.LBB0_1057:
	s_or_b64 exec, exec, s[0:1]
	v_lshlrev_b32_e32 v211, 2, v149
	v_mov_b32_e32 v212, 0
	v_cmp_gt_u32_e32 vcc, 64, v149
	s_and_saveexec_b64 s[100:101], vcc
	ds_write_b32 v211, v212 offset:41728
	s_mov_b64 exec, s[100:101]
	s_movk_i32 s100, 0xc0
	v_cmp_gt_u32_e32 vcc, s100, v149
	s_and_saveexec_b64 s[100:101], vcc
	ds_write_b32 v211, v212 offset:43844
	s_mov_b64 exec, s[100:101]
	v_and_b32_e32 v3, 15, v2
	v_ashrrev_i32_e32 v14, 1, v2
	s_movk_i32 s0, 0xffe0
	v_bfe_u32 v15, v2, 4, 2
	v_and_or_b32 v4, v14, s0, v3
	v_readlane_b32 s0, v248, 29
	v_lshlrev_b32_e32 v0, 4, v15
	v_readlane_b32 s1, v248, 30
	v_ashrrev_i32_e32 v5, 31, v4
	v_lshlrev_b64 v[156:157], 10, v[4:5]
	v_lshl_add_u64 v[6:7], s[0:1], 0, v[0:1]
	v_or_b32_e32 v4, 16, v4
	v_ashrrev_i32_e32 v0, 31, v2
	v_ashrrev_i32_e32 v5, 31, v4
	v_lshrrev_b32_e32 v0, 29, v0
	v_lshlrev_b64 v[154:155], 10, v[4:5]
	v_add_u32_e32 v0, v2, v0
	s_movk_i32 s0, 0x200
	v_lshl_add_u64 v[8:9], v[6:7], 0, v[156:157]
	v_lshl_add_u64 v[4:5], v[6:7], 0, v[154:155]
	s_waitcnt vmcnt(10)
	v_ashrrev_i32_e32 v48, 3, v0
	v_cmp_gt_i32_e64 s[48:49], s0, v2
	global_load_dwordx4 v[16:19], v[8:9], off
	global_load_dwordx4 v[20:23], v[8:9], off offset:64
	global_load_dwordx4 v[24:27], v[4:5], off
	global_load_dwordx4 v[28:31], v[4:5], off offset:64
	v_cndmask_b32_e64 v4, 0, v48, s[48:49]
	v_lshlrev_b32_e32 v0, 3, v4
	v_sub_u32_e32 v49, v2, v0
	v_ashrrev_i32_e32 v5, 31, v4
	v_cndmask_b32_e64 v13, 0, v49, s[48:49]
	v_lshlrev_b64 v[6:7], 10, v[4:5]
	v_lshl_add_u64 v[8:9], s[56:57], 0, v[6:7]
	v_lshlrev_b32_e32 v6, 3, v13
	v_readlane_b32 s0, v248, 33
	v_ashrrev_i32_e32 v7, 31, v6
	v_readlane_b32 s1, v248, 34
	v_ashrrev_i32_e32 v12, 3, v2
	s_waitcnt vmcnt(10)
	v_and_b32_e32 v40, 7, v2
	v_lshl_add_u64 v[10:11], v[6:7], 1, v[8:9]
	v_mov_b64_e32 v[8:9], s[0:1]
	v_mad_i64_i32 v[8:9], s[0:1], v12, s63, v[8:9]
	v_lshlrev_b32_e32 v0, 4, v40
	v_lshl_add_u64 v[8:9], v[8:9], 0, v[0:1]
	global_load_dwordx4 v[32:35], v[10:11], off
	global_load_dwordx4 v[36:39], v[8:9], off
	v_lshlrev_b32_e32 v5, 3, v40
	s_cmp_gt_i32 s51, -11
	v_lshlrev_b32_e32 v8, 1, v5
	s_cbranch_scc0 .LBB0_1059
	v_readlane_b32 s0, v248, 33
	v_readlane_b32 s1, v248, 34
	v_add_u32_e32 v5, 64, v12
	v_add_co_u32_e32 v10, vcc, 0x10000, v10
	v_mov_b64_e32 v[40:41], s[0:1]
	v_mad_i64_i32 v[40:41], s[0:1], v5, s63, v[40:41]
	v_mov_b32_e32 v9, v1
	v_addc_co_u32_e32 v11, vcc, 0, v11, vcc
	s_waitcnt vmcnt(11)
	v_lshl_add_u64 v[44:45], v[40:41], 0, v[8:9]
	global_load_dwordx4 v[40:43], v[10:11], off
	s_nop 0
	global_load_dwordx4 v[44:47], v[44:45], off

; template <int DQK, bool NA, bool SMAX, int LDV> ...
;     ...
;           const int base = (kr - qr + 7) * 31 + 15 - qc;
;           float bv[4][4];
; #pragma unroll
;           for (int kt = 0; kt < 4; ++kt)
; #pragma unroll
;             for (int j = 0; j < 4; ++j) bv[kt][j] = rpbl[min(max(base + kt * 16 + fq * 4 + j, 0), 464)];
; #pragma unroll
;           for (int kt = 0; kt < 4; ++kt)
; #pragma unroll
;             for (int j = 0; j < 4; ++j) {
;               const int kc = kt * 16 + fq * 4 + j;
;               const float okf = (rowok && (kc >= cst) && (kc < cst + 16)) ? 1.f : 0.f;
;               const float pv = __builtin_amdgcn_exp2f(__builtin_fmaf(s[kt][qt][j], c1, bv[kt][j] - m0)) * okf;
;               s[kt][qt][j] = pv; sum += pv;
;             }
.LBB0_1069:
	s_andn2_b64 vcc, exec, s[26:27]
	s_cbranch_vccnz .LBB0_1071
	v_subrev_u32_e32 v0, 31, v208
	s_movk_i32 s101, 0x100
	v_lshl_add_u32 v211, v0, 2, s101
	ds_read_b32 v104, v211 offset:41728
	ds_read_b32 v105, v211 offset:41732
	ds_read_b32 v106, v211 offset:41736
	ds_read_b32 v107, v211 offset:41740
	ds_read_b32 v108, v211 offset:41792
	ds_read_b32 v109, v211 offset:41796
	ds_read_b32 v110, v211 offset:41800
	ds_read_b32 v111, v211 offset:41804
	ds_read_b32 v112, v211 offset:41856
	ds_read_b32 v113, v211 offset:41860
	ds_read_b32 v114, v211 offset:41864
	ds_read_b32 v115, v211 offset:41868
	ds_read_b32 v128, v211 offset:41920
	s_add_i32 s26, s19, s43
	s_add_i32 s26, s26, -4
	ds_read_b32 v129, v211 offset:41924
	v_cmp_ge_i32_e32 vcc, s26, v164
	v_cmp_lt_i32_e64 s[40:41], s26, v163
	s_waitcnt lgkmcnt(13)
	s_or_b64 s[26:27], s[40:41], vcc
	v_fmac_f32_e32 v104, 0x3e38aa3b, v144
	s_waitcnt lgkmcnt(12)
	s_or_b64 s[40:41], s[26:27], s[58:59]
	v_exp_f32_e32 v130, v104
	v_fmac_f32_e32 v105, 0x3e38aa3b, v145
	ds_read_b32 v2, v211 offset:41928
	ds_read_b32 v3, v211 offset:41932
	v_cndmask_b32_e64 v0, 1.0, 0, s[40:41]
	v_readlane_b32 s40, v248, 21
	v_exp_f32_e32 v131, v105
	v_readlane_b32 s41, v248, 22
	s_or_b64 s[40:41], s[26:27], s[40:41]
	s_waitcnt lgkmcnt(13)
	v_mul_f32_e32 v104, v0, v130
	v_fma_f32 v0, v0, v130, 0
	v_cndmask_b32_e64 v130, 1.0, 0, s[40:41]
	v_fmac_f32_e32 v106, 0x3e38aa3b, v146
	v_mul_f32_e32 v105, v130, v131
	v_fmac_f32_e32 v0, v130, v131
	v_exp_f32_e32 v131, v106
	s_or_b64 s[40:41], s[26:27], s[52:53]
	s_waitcnt lgkmcnt(12)
	v_cndmask_b32_e64 v130, 1.0, 0, s[40:41]
	v_fmac_f32_e32 v107, 0x3e38aa3b, v147
	v_mul_f32_e32 v106, v130, v131
	v_fmac_f32_e32 v0, v130, v131
	v_exp_f32_e32 v131, v107
	s_or_b64 s[40:41], s[26:27], s[54:55]
	s_waitcnt lgkmcnt(11)
	v_cndmask_b32_e64 v130, 1.0, 0, s[40:41]
	v_fmac_f32_e32 v108, 0x3e38aa3b, v140
	v_mul_f32_e32 v107, v130, v131
	v_fmac_f32_e32 v0, v130, v131
	v_exp_f32_e32 v131, v108
	s_or_b64 s[40:41], s[26:27], s[56:57]
	s_waitcnt lgkmcnt(10)
	v_cndmask_b32_e64 v130, v165, 0, s[40:41]
	v_fmac_f32_e32 v109, 0x3e38aa3b, v141
	v_mul_f32_e32 v108, v130, v131
	v_fmac_f32_e32 v0, v130, v131
	v_exp_f32_e32 v131, v109
	s_or_b64 s[40:41], s[26:27], s[60:61]
	s_waitcnt lgkmcnt(9)
	v_cndmask_b32_e64 v130, v166, 0, s[40:41]
	v_fmac_f32_e32 v110, 0x3e38aa3b, v142
	v_mul_f32_e32 v109, v130, v131
	v_fmac_f32_e32 v0, v130, v131
	v_exp_f32_e32 v131, v110
	s_or_b64 s[40:41], s[26:27], s[50:51]
	s_waitcnt lgkmcnt(8)
	v_cndmask_b32_e64 v130, v168, 0, s[40:41]
	v_fmac_f32_e32 v111, 0x3e38aa3b, v143
	v_mul_f32_e32 v110, v130, v131
	v_fmac_f32_e32 v0, v130, v131
	v_exp_f32_e32 v131, v111
	s_or_b64 s[40:41], s[26:27], s[64:65]
	s_waitcnt lgkmcnt(7)
	v_cndmask_b32_e64 v130, v169, 0, s[40:41]
	v_fmac_f32_e32 v112, 0x3e38aa3b, v136
	v_mul_f32_e32 v111, v130, v131
	v_fmac_f32_e32 v0, v130, v131
	v_exp_f32_e32 v131, v112
	s_or_b64 s[40:41], s[26:27], s[66:67]
	s_waitcnt lgkmcnt(6)
	v_cndmask_b32_e64 v130, v170, 0, s[40:41]
	v_fmac_f32_e32 v113, 0x3e38aa3b, v137
	v_mul_f32_e32 v112, v130, v131
	v_fmac_f32_e32 v0, v130, v131
	v_exp_f32_e32 v131, v113
	s_or_b64 s[40:41], s[26:27], s[68:69]
	s_waitcnt lgkmcnt(5)
	v_cndmask_b32_e64 v130, v171, 0, s[40:41]
	v_fmac_f32_e32 v114, 0x3e38aa3b, v138
	v_mul_f32_e32 v113, v130, v131
	v_fmac_f32_e32 v0, v130, v131
	v_exp_f32_e32 v131, v114
	s_or_b64 s[40:41], s[26:27], s[70:71]
	s_waitcnt lgkmcnt(4)
	v_cndmask_b32_e64 v130, v172, 0, s[40:41]
	v_fmac_f32_e32 v115, 0x3e38aa3b, v139
	v_mul_f32_e32 v114, v130, v131
	v_fmac_f32_e32 v0, v130, v131
	v_exp_f32_e32 v131, v115
	s_or_b64 s[40:41], s[26:27], s[72:73]
	s_waitcnt lgkmcnt(3)
	v_cndmask_b32_e64 v130, v173, 0, s[40:41]
	v_fmac_f32_e32 v128, 0x3e38aa3b, v132
	v_mul_f32_e32 v115, v130, v131
	v_fmac_f32_e32 v0, v130, v131
	v_exp_f32_e32 v131, v128
	s_waitcnt lgkmcnt(2)
	v_cndmask_b32_e64 v130, v174, 0, s[26:27]
	v_fmac_f32_e32 v129, 0x3e38aa3b, v133
	s_waitcnt lgkmcnt(1)
	v_mul_f32_e32 v128, v130, v131
	v_fmac_f32_e32 v0, v130, v131
	v_exp_f32_e32 v131, v129
	v_fmac_f32_e32 v2, 0x3e38aa3b, v134
	s_waitcnt lgkmcnt(0)
	v_exp_f32_e32 v2, v2
	v_fmac_f32_e32 v3, 0x3e38aa3b, v135
	v_exp_f32_e32 v3, v3
	v_cndmask_b32_e64 v130, v175, 0, s[26:27]
	v_mul_f32_e32 v129, v130, v131
	v_fmac_f32_e32 v0, v130, v131
	v_cndmask_b32_e64 v131, v176, 0, s[26:27]
	v_mul_f32_e32 v130, v131, v2
	v_fmac_f32_e32 v0, v131, v2
	v_cndmask_b32_e64 v2, v177, 0, s[26:27]
	v_mul_f32_e32 v131, v2, v3
	v_fmac_f32_e32 v0, v2, v3

; template <int DQK, bool NA, bool SMAX, int LDV> ...
;     ...
;           const int base = (kr - qr + 7) * 31 + 15 - qc;
;           float bv[4][4];
; #pragma unroll
;           for (int kt = 0; kt < 4; ++kt)
; #pragma unroll
;             for (int j = 0; j < 4; ++j) bv[kt][j] = rpbl[min(max(base + kt * 16 + fq * 4 + j, 0), 464)];
; #pragma unroll
;           for (int kt = 0; kt < 4; ++kt)
; #pragma unroll
;             for (int j = 0; j < 4; ++j) {
;               const int kc = kt * 16 + fq * 4 + j;
;               const float okf = (rowok && (kc >= cst) && (kc < cst + 16)) ? 1.f : 0.f;
;               const float pv = __builtin_amdgcn_exp2f(__builtin_fmaf(s[kt][qt][j], c1, bv[kt][j] - m0)) * okf;
;               s[kt][qt][j] = pv; sum += pv;
;             }
.LBB0_1073:
	s_andn2_b64 vcc, exec, s[0:1]
	s_cbranch_vccnz .LBB0_1075
	v_subrev_u32_e32 v2, 47, v208
	s_movk_i32 s101, 0x100
	v_lshl_add_u32 v211, v2, 2, s101
	ds_read_b32 v132, v211 offset:41728
	ds_read_b32 v133, v211 offset:41732
	ds_read_b32 v134, v211 offset:41736
	ds_read_b32 v135, v211 offset:41740
	ds_read_b32 v136, v211 offset:41792
	ds_read_b32 v137, v211 offset:41796
	ds_read_b32 v138, v211 offset:41800
	ds_read_b32 v139, v211 offset:41804
	ds_read_b32 v140, v211 offset:41856
	ds_read_b32 v141, v211 offset:41860
	ds_read_b32 v142, v211 offset:41864
	ds_read_b32 v143, v211 offset:41868
	ds_read_b32 v144, v211 offset:41920
	s_add_i32 s0, s19, s43
	s_waitcnt lgkmcnt(12)
	s_add_i32 s26, s0, -4
	ds_read_b32 v145, v211 offset:41924
	v_fmac_f32_e32 v132, 0x3e38aa3b, v124
	s_waitcnt lgkmcnt(12)
	v_cmp_ge_i32_e64 s[0:1], s26, v164
	v_cmp_lt_i32_e32 vcc, s26, v163
	v_exp_f32_e32 v124, v132
	v_fmac_f32_e32 v133, 0x3e38aa3b, v125
	s_or_b64 s[0:1], vcc, s[0:1]
	v_exp_f32_e32 v125, v133
	s_or_b64 s[26:27], s[0:1], s[82:83]
	ds_read_b32 v3, v211 offset:41928
	ds_read_b32 v147, v211 offset:41932
	v_cndmask_b32_e64 v2, 1.0, 0, s[26:27]
	s_or_b64 s[26:27], s[0:1], s[74:75]
	v_mul_f32_e32 v132, v2, v124
	v_fma_f32 v2, v2, v124, 0
	v_cndmask_b32_e64 v124, 1.0, 0, s[26:27]
	v_mul_f32_e32 v133, v124, v125
	v_fmac_f32_e32 v2, v124, v125
	s_waitcnt lgkmcnt(13)
	v_fma_f32 v125, v126, s62, v134
	v_exp_f32_e32 v125, v125
	s_or_b64 s[26:27], s[0:1], s[76:77]
	v_cndmask_b32_e64 v124, 1.0, 0, s[26:27]
	s_or_b64 s[26:27], s[0:1], s[78:79]
	v_mul_f32_e32 v134, v124, v125
	v_fmac_f32_e32 v2, v124, v125
	s_waitcnt lgkmcnt(12)
	v_fma_f32 v125, v127, s62, v135
	v_exp_f32_e32 v125, v125
	v_cndmask_b32_e64 v124, 1.0, 0, s[26:27]
	s_or_b64 s[26:27], s[0:1], s[80:81]
	s_waitcnt lgkmcnt(1)
	v_mul_f32_e32 v135, v124, v125
	v_fmac_f32_e32 v2, v124, v125
	v_fma_f32 v125, v120, s62, v136
	v_exp_f32_e32 v120, v125
	v_cndmask_b32_e64 v124, v178, 0, s[26:27]
	s_or_b64 s[26:27], s[0:1], s[84:85]
	v_fmac_f32_e32 v3, 0x3e38aa3b, v102
	v_mul_f32_e32 v136, v124, v120
	v_fmac_f32_e32 v2, v124, v120
	v_fma_f32 v124, v121, s62, v137
	v_exp_f32_e32 v121, v124
	v_cndmask_b32_e64 v120, v179, 0, s[26:27]
	s_or_b64 s[26:27], s[0:1], s[86:87]
	v_exp_f32_e32 v3, v3
	v_mul_f32_e32 v137, v120, v121
	v_fmac_f32_e32 v2, v120, v121
	v_fma_f32 v121, v122, s62, v138
	v_exp_f32_e32 v121, v121
	v_cndmask_b32_e64 v120, v180, 0, s[26:27]
	s_or_b64 s[26:27], s[0:1], s[88:89]
	v_mul_f32_e32 v138, v120, v121
	v_fmac_f32_e32 v2, v120, v121
	v_fma_f32 v121, v123, s62, v139
	v_exp_f32_e32 v121, v121
	v_cndmask_b32_e64 v120, v181, 0, s[26:27]
	s_or_b64 s[26:27], s[0:1], s[90:91]
	v_mul_f32_e32 v139, v120, v121
	v_fmac_f32_e32 v2, v120, v121
	v_fma_f32 v121, v116, s62, v140
	v_exp_f32_e32 v116, v121
	v_cndmask_b32_e64 v120, v182, 0, s[26:27]
	s_or_b64 s[26:27], s[0:1], s[92:93]
	v_mul_f32_e32 v140, v120, v116
	v_fmac_f32_e32 v2, v120, v116
	v_fma_f32 v120, v117, s62, v141
	v_exp_f32_e32 v117, v120
	v_cndmask_b32_e64 v116, v183, 0, s[26:27]
	s_or_b64 s[26:27], s[0:1], s[94:95]
	v_mul_f32_e32 v141, v116, v117
	v_fmac_f32_e32 v2, v116, v117
	v_fma_f32 v117, v118, s62, v142
	v_exp_f32_e32 v117, v117
	v_cndmask_b32_e64 v116, v184, 0, s[26:27]
	s_or_b64 s[26:27], s[0:1], s[96:97]
	v_mul_f32_e32 v142, v116, v117
	v_fmac_f32_e32 v2, v116, v117
	v_fma_f32 v117, v119, s62, v143
	v_exp_f32_e32 v117, v117
	v_cndmask_b32_e64 v116, v185, 0, s[26:27]
	v_mul_f32_e32 v143, v116, v117
	v_fmac_f32_e32 v2, v116, v117
	v_fma_f32 v117, v100, s62, v144
	v_exp_f32_e32 v100, v117
	v_cndmask_b32_e64 v116, v186, 0, s[0:1]
	v_mul_f32_e32 v144, v116, v100
	v_fmac_f32_e32 v2, v116, v100
	v_fma_f32 v116, v101, s62, v145
	v_exp_f32_e32 v101, v116
	v_cndmask_b32_e64 v100, v187, 0, s[0:1]
	v_mul_f32_e32 v145, v100, v101
	v_fmac_f32_e32 v2, v100, v101
	v_cndmask_b32_e64 v100, v189, 0, s[0:1]
	v_mul_f32_e32 v146, v100, v3
	v_fmac_f32_e32 v2, v100, v3
	s_waitcnt lgkmcnt(0)
	v_fma_f32 v100, v103, s62, v147
	v_exp_f32_e32 v100, v100
	v_cndmask_b32_e64 v3, v203, 0, s[0:1]
	v_mul_f32_e32 v147, v3, v100
	v_fmac_f32_e32 v2, v3, v100

; template <int DQK, bool NA, bool SMAX, int LDV> ...
;     ...
;           const int base = (kr - qr + 7) * 31 + 15 - qc;
;           float bv[4][4];
; #pragma unroll
;           for (int kt = 0; kt < 4; ++kt)
; #pragma unroll
;             for (int j = 0; j < 4; ++j) bv[kt][j] = rpbl[min(max(base + kt * 16 + fq * 4 + j, 0), 464)];
; #pragma unroll
;           for (int kt = 0; kt < 4; ++kt)
; #pragma unroll
;             for (int j = 0; j < 4; ++j) {
;               const int kc = kt * 16 + fq * 4 + j;
;               const float okf = (rowok && (kc >= cst) && (kc < cst + 16)) ? 1.f : 0.f;
;               const float pv = __builtin_amdgcn_exp2f(__builtin_fmaf(s[kt][qt][j], c1, bv[kt][j] - m0)) * okf;
;               s[kt][qt][j] = pv; sum += pv;
;             }
.LBB0_1085:
	s_movk_i32 s101, 0x100
	v_lshl_add_u32 v211, v208, 2, s101
	ds_read_b32 v0, v211 offset:41728
	ds_read_b32 v105, v211 offset:41732
	ds_read_b32 v3, v211 offset:41932
	ds_read_b32 v106, v211 offset:41736
	s_add_i32 s0, s19, s43
	s_add_i32 s0, s0, -3
	v_cmp_ge_i32_e32 vcc, s0, v164
	v_cmp_lt_i32_e64 s[0:1], s0, v163
	s_waitcnt lgkmcnt(3)
	ds_read_b32 v107, v211 offset:41740
	s_or_b64 s[0:1], s[0:1], vcc
	v_fmac_f32_e32 v0, 0x3e38aa3b, v144
	s_waitcnt lgkmcnt(3)
	s_or_b64 s[26:27], s[0:1], s[58:59]
	v_exp_f32_e32 v0, v0
	v_fmac_f32_e32 v105, 0x3e38aa3b, v145
	v_cndmask_b32_e64 v130, 1.0, 0, s[26:27]
	v_readlane_b32 s26, v248, 21
	v_exp_f32_e32 v131, v105
	v_readlane_b32 s27, v248, 22
	ds_read_b32 v108, v211 offset:41792
	s_or_b64 s[26:27], s[0:1], s[26:27]
	s_waitcnt lgkmcnt(2)
	v_mul_f32_e32 v104, v130, v0
	v_fma_f32 v0, v130, v0, 0
	v_cndmask_b32_e64 v130, 1.0, 0, s[26:27]
	v_fmac_f32_e32 v106, 0x3e38aa3b, v146
	v_mul_f32_e32 v105, v130, v131
	v_fmac_f32_e32 v0, v130, v131
	v_exp_f32_e32 v131, v106
	ds_read_b32 v109, v211 offset:41796
	s_or_b64 s[26:27], s[0:1], s[52:53]
	s_waitcnt lgkmcnt(2)
	v_cndmask_b32_e64 v130, 1.0, 0, s[26:27]
	v_fmac_f32_e32 v107, 0x3e38aa3b, v147
	v_mul_f32_e32 v106, v130, v131
	v_fmac_f32_e32 v0, v130, v131
	v_exp_f32_e32 v131, v107
	ds_read_b32 v110, v211 offset:41800
	s_or_b64 s[26:27], s[0:1], s[54:55]
	s_waitcnt lgkmcnt(2)
	v_cndmask_b32_e64 v130, 1.0, 0, s[26:27]
	v_fmac_f32_e32 v108, 0x3e38aa3b, v140
	v_mul_f32_e32 v107, v130, v131
	v_fmac_f32_e32 v0, v130, v131
	v_exp_f32_e32 v131, v108
	ds_read_b32 v111, v211 offset:41804
	s_or_b64 s[26:27], s[0:1], s[56:57]
	s_waitcnt lgkmcnt(2)
	v_cndmask_b32_e64 v130, v165, 0, s[26:27]
	v_fmac_f32_e32 v109, 0x3e38aa3b, v141
	v_mul_f32_e32 v108, v130, v131
	v_fmac_f32_e32 v0, v130, v131
	v_exp_f32_e32 v131, v109
	ds_read_b32 v112, v211 offset:41856
	s_or_b64 s[26:27], s[0:1], s[60:61]
	s_waitcnt lgkmcnt(2)
	v_cndmask_b32_e64 v130, v166, 0, s[26:27]
	v_fmac_f32_e32 v110, 0x3e38aa3b, v142
	v_mul_f32_e32 v109, v130, v131
	v_fmac_f32_e32 v0, v130, v131
	v_exp_f32_e32 v131, v110
	ds_read_b32 v113, v211 offset:41860
	s_or_b64 s[26:27], s[0:1], s[50:51]
	s_waitcnt lgkmcnt(2)
	v_cndmask_b32_e64 v130, v168, 0, s[26:27]
	v_fmac_f32_e32 v111, 0x3e38aa3b, v143
	v_mul_f32_e32 v110, v130, v131
	v_fmac_f32_e32 v0, v130, v131
	v_exp_f32_e32 v131, v111
	ds_read_b32 v114, v211 offset:41864
	s_or_b64 s[26:27], s[0:1], s[64:65]
	s_waitcnt lgkmcnt(2)
	v_cndmask_b32_e64 v130, v169, 0, s[26:27]
	v_fmac_f32_e32 v112, 0x3e38aa3b, v136
	v_mul_f32_e32 v111, v130, v131
	v_fmac_f32_e32 v0, v130, v131
	v_exp_f32_e32 v131, v112
	ds_read_b32 v115, v211 offset:41868
	s_or_b64 s[26:27], s[0:1], s[66:67]
	s_waitcnt lgkmcnt(2)
	v_cndmask_b32_e64 v130, v170, 0, s[26:27]
	v_fmac_f32_e32 v113, 0x3e38aa3b, v137
	v_mul_f32_e32 v112, v130, v131
	v_fmac_f32_e32 v0, v130, v131
	v_exp_f32_e32 v131, v113
	ds_read_b32 v128, v211 offset:41920
	s_or_b64 s[26:27], s[0:1], s[68:69]
	s_waitcnt lgkmcnt(2)
	v_cndmask_b32_e64 v130, v171, 0, s[26:27]
	v_fmac_f32_e32 v114, 0x3e38aa3b, v138
	v_mul_f32_e32 v113, v130, v131
	v_fmac_f32_e32 v0, v130, v131
	v_exp_f32_e32 v131, v114
	ds_read_b32 v129, v211 offset:41924
	s_or_b64 s[26:27], s[0:1], s[70:71]
	s_waitcnt lgkmcnt(2)
	v_cndmask_b32_e64 v130, v172, 0, s[26:27]
	v_fmac_f32_e32 v115, 0x3e38aa3b, v139
	v_mul_f32_e32 v114, v130, v131
	v_fmac_f32_e32 v0, v130, v131
	v_exp_f32_e32 v131, v115
	ds_read_b32 v2, v211 offset:41928
	s_or_b64 s[26:27], s[0:1], s[72:73]
	s_waitcnt lgkmcnt(2)
	v_cndmask_b32_e64 v130, v173, 0, s[26:27]
	v_fmac_f32_e32 v128, 0x3e38aa3b, v132
	v_mul_f32_e32 v115, v130, v131
	v_fmac_f32_e32 v0, v130, v131
	v_exp_f32_e32 v131, v128
	s_waitcnt lgkmcnt(1)
	v_cndmask_b32_e64 v130, v174, 0, s[0:1]
	v_fmac_f32_e32 v129, 0x3e38aa3b, v133
	s_waitcnt lgkmcnt(0)
	v_mul_f32_e32 v128, v130, v131
	v_fmac_f32_e32 v0, v130, v131
	v_exp_f32_e32 v131, v129
	v_fmac_f32_e32 v2, 0x3e38aa3b, v134
	v_exp_f32_e32 v2, v2
	v_fmac_f32_e32 v3, 0x3e38aa3b, v135
	v_exp_f32_e32 v3, v3
	v_cndmask_b32_e64 v130, v175, 0, s[0:1]
	v_mul_f32_e32 v129, v130, v131
	v_fmac_f32_e32 v0, v130, v131
	v_cndmask_b32_e64 v131, v176, 0, s[0:1]
	v_mul_f32_e32 v130, v131, v2
	v_fmac_f32_e32 v0, v131, v2
	v_cndmask_b32_e64 v2, v177, 0, s[0:1]
	v_mul_f32_e32 v131, v2, v3
	v_fmac_f32_e32 v0, v2, v3

; template <int DQK, bool NA, bool SMAX, int LDV> ...
;     ...
;           const int base = (kr - qr + 7) * 31 + 15 - qc;
;           float bv[4][4];
; #pragma unroll
;           for (int kt = 0; kt < 4; ++kt)
; #pragma unroll
;             for (int j = 0; j < 4; ++j) bv[kt][j] = rpbl[min(max(base + kt * 16 + fq * 4 + j, 0), 464)];
; #pragma unroll
;           for (int kt = 0; kt < 4; ++kt)
; #pragma unroll
;             for (int j = 0; j < 4; ++j) {
;               const int kc = kt * 16 + fq * 4 + j;
;               const float okf = (rowok && (kc >= cst) && (kc < cst + 16)) ? 1.f : 0.f;
;               const float pv = __builtin_amdgcn_exp2f(__builtin_fmaf(s[kt][qt][j], c1, bv[kt][j] - m0)) * okf;
;               s[kt][qt][j] = pv; sum += pv;
;             }
.LBB0_1089:
	v_add_u32_e32 v2, -16, v208
	s_movk_i32 s101, 0x100
	v_lshl_add_u32 v211, v2, 2, s101
	ds_read_b32 v132, v211 offset:41728
	ds_read_b32 v133, v211 offset:41732
	ds_read_b32 v134, v211 offset:41736
	ds_read_b32 v135, v211 offset:41740
	ds_read_b32 v136, v211 offset:41792
	ds_read_b32 v137, v211 offset:41796
	ds_read_b32 v138, v211 offset:41800
	ds_read_b32 v139, v211 offset:41804
	ds_read_b32 v140, v211 offset:41856
	ds_read_b32 v141, v211 offset:41860
	ds_read_b32 v142, v211 offset:41864
	ds_read_b32 v143, v211 offset:41868
	ds_read_b32 v144, v211 offset:41920
	s_add_i32 s0, s19, s43
	s_waitcnt lgkmcnt(12)
	s_add_i32 s0, s0, -3
	ds_read_b32 v145, v211 offset:41924
	v_fmac_f32_e32 v132, 0x3e38aa3b, v124
	s_waitcnt lgkmcnt(12)
	v_cmp_ge_i32_e32 vcc, s0, v164
	v_cmp_lt_i32_e64 s[0:1], s0, v163
	v_exp_f32_e32 v124, v132
	v_fmac_f32_e32 v133, 0x3e38aa3b, v125
	s_or_b64 s[0:1], s[0:1], vcc
	v_exp_f32_e32 v125, v133
	s_or_b64 s[26:27], s[0:1], s[82:83]
	ds_read_b32 v3, v211 offset:41928
	ds_read_b32 v147, v211 offset:41932
	v_cndmask_b32_e64 v2, 1.0, 0, s[26:27]
	s_or_b64 s[26:27], s[0:1], s[74:75]
	v_mul_f32_e32 v132, v2, v124
	v_fma_f32 v2, v2, v124, 0
	v_cndmask_b32_e64 v124, 1.0, 0, s[26:27]
	v_mul_f32_e32 v133, v124, v125
	v_fmac_f32_e32 v2, v124, v125
	s_waitcnt lgkmcnt(13)
	v_fma_f32 v125, v126, s62, v134
	v_exp_f32_e32 v125, v125
	s_or_b64 s[26:27], s[0:1], s[76:77]
	v_cndmask_b32_e64 v124, 1.0, 0, s[26:27]
	s_or_b64 s[26:27], s[0:1], s[78:79]
	v_mul_f32_e32 v134, v124, v125
	v_fmac_f32_e32 v2, v124, v125
	s_waitcnt lgkmcnt(12)
	v_fma_f32 v125, v127, s62, v135
	v_exp_f32_e32 v125, v125
	v_cndmask_b32_e64 v124, 1.0, 0, s[26:27]
	s_or_b64 s[26:27], s[0:1], s[80:81]
	s_waitcnt lgkmcnt(1)
	v_mul_f32_e32 v135, v124, v125
	v_fmac_f32_e32 v2, v124, v125
	v_fma_f32 v125, v120, s62, v136
	v_exp_f32_e32 v120, v125
	v_cndmask_b32_e64 v124, v178, 0, s[26:27]
	s_or_b64 s[26:27], s[0:1], s[84:85]
	v_fmac_f32_e32 v3, 0x3e38aa3b, v102
	v_mul_f32_e32 v136, v124, v120
	v_fmac_f32_e32 v2, v124, v120
	v_fma_f32 v124, v121, s62, v137
	v_exp_f32_e32 v121, v124
	v_cndmask_b32_e64 v120, v179, 0, s[26:27]
	s_or_b64 s[26:27], s[0:1], s[86:87]
	v_exp_f32_e32 v3, v3
	v_mul_f32_e32 v137, v120, v121
	v_fmac_f32_e32 v2, v120, v121
	v_fma_f32 v121, v122, s62, v138
	v_exp_f32_e32 v121, v121
	v_cndmask_b32_e64 v120, v180, 0, s[26:27]
	s_or_b64 s[26:27], s[0:1], s[88:89]
	v_mul_f32_e32 v138, v120, v121
	v_fmac_f32_e32 v2, v120, v121
	v_fma_f32 v121, v123, s62, v139
	v_exp_f32_e32 v121, v121
	v_cndmask_b32_e64 v120, v181, 0, s[26:27]
	s_or_b64 s[26:27], s[0:1], s[90:91]
	v_mul_f32_e32 v139, v120, v121
	v_fmac_f32_e32 v2, v120, v121
	v_fma_f32 v121, v116, s62, v140
	v_exp_f32_e32 v116, v121
	v_cndmask_b32_e64 v120, v182, 0, s[26:27]
	s_or_b64 s[26:27], s[0:1], s[92:93]
	v_mul_f32_e32 v140, v120, v116
	v_fmac_f32_e32 v2, v120, v116
	v_fma_f32 v120, v117, s62, v141
	v_exp_f32_e32 v117, v120
	v_cndmask_b32_e64 v116, v183, 0, s[26:27]
	s_or_b64 s[26:27], s[0:1], s[94:95]
	v_mul_f32_e32 v141, v116, v117
	v_fmac_f32_e32 v2, v116, v117
	v_fma_f32 v117, v118, s62, v142
	v_exp_f32_e32 v117, v117
	v_cndmask_b32_e64 v116, v184, 0, s[26:27]
	s_or_b64 s[26:27], s[0:1], s[96:97]
	v_mul_f32_e32 v142, v116, v117
	v_fmac_f32_e32 v2, v116, v117
	v_fma_f32 v117, v119, s62, v143
	v_exp_f32_e32 v117, v117
	v_cndmask_b32_e64 v116, v185, 0, s[26:27]
	v_mul_f32_e32 v143, v116, v117
	v_fmac_f32_e32 v2, v116, v117
	v_fma_f32 v117, v100, s62, v144
	v_exp_f32_e32 v100, v117
	v_cndmask_b32_e64 v116, v186, 0, s[0:1]
	v_mul_f32_e32 v144, v116, v100
	v_fmac_f32_e32 v2, v116, v100
	v_fma_f32 v116, v101, s62, v145
	v_exp_f32_e32 v101, v116
	v_cndmask_b32_e64 v100, v187, 0, s[0:1]
	v_mul_f32_e32 v145, v100, v101
	v_fmac_f32_e32 v2, v100, v101
	v_cndmask_b32_e64 v100, v189, 0, s[0:1]
	v_mul_f32_e32 v146, v100, v3
	v_fmac_f32_e32 v2, v100, v3
	s_waitcnt lgkmcnt(0)
	v_fma_f32 v100, v103, s62, v147
	v_exp_f32_e32 v100, v100
	v_cndmask_b32_e64 v3, v203, 0, s[0:1]
	v_mul_f32_e32 v147, v3, v100
	v_fmac_f32_e32 v2, v3, v100
